# attention loops: back edge rotated out of the post-barrier path (loop-carried mov before the barrier, single conditional back branch); row-max head 3 ops -> 1
# baseline (speedup 1.0000x reference)
; __device__ __forceinline__ void attn_unit(LAS unsigned char* lds, int b, int h, int qb, const bf16_t* Q, const bf16_t* KF, const bf16_t* VT,
;                                           const float* gout, bf16_t* MIXED, int wave, int lane) {
;     ...
;             float mt = sacc[0][0];
; #pragma unroll
;             for (int kb = 0; kb < 2; ++kb)
; #pragma unroll
;                 for (int i = 0; i < 16; ++i) mt = fmaxf(mt, sacc[kb][i]);
;             mt = fmaxf(mt, __shfl_xor(mt, 32));
;             __builtin_amdgcn_sched_barrier(0);
;             if (__builtin_amdgcn_ballot_w64(mt > m_run + 8.f) != 0ull) {
;                 const float mn = fmaxf(m_run, mt);
;                 const float alpha = __builtin_amdgcn_exp2f(m_run - mn);
;                 m_run = mn;
;                 l_run *= alpha;
; #pragma unroll
;                 for (int db = 0; db < 4; ++db)
; #pragma unroll
;                     for (int i = 0; i < 16; ++i) asm volatile("v_mul_f32 %0, %0, %1" : "+v"(oacc[db][i]) : "v"(alpha));
;             }
.LBB0_455:
	v_max_f32_e32 v108, v64, v65
	v_max3_f32 v108, v108, v66, v67
	v_max3_f32 v108, v108, v68, v69
	v_max3_f32 v108, v108, v70, v71
	v_max3_f32 v108, v108, v72, v73
	v_max3_f32 v108, v108, v74, v75
	v_max3_f32 v108, v108, v76, v77
	v_max3_f32 v108, v108, v78, v79
	v_max3_f32 v108, v108, v80, v81
	v_max3_f32 v108, v108, v82, v83
	v_max3_f32 v108, v108, v84, v85
	v_max3_f32 v108, v108, v86, v87
	v_max3_f32 v108, v108, v88, v89
	v_max3_f32 v108, v108, v90, v91
	v_max3_f32 v108, v108, v92, v93
	v_max3_f32 v108, v108, v94, v95
	v_mov_b32_e32 v109, v108
	s_nop 1
	v_permlane32_swap_b32_e32 v109, v108
	v_max_f32_e32 v108, v108, v109
	v_add_f32_e32 v109, 0x41000000, v220
	v_cmp_gt_f32_e32 vcc, v108, v109
	s_cbranch_vccz .LBB0_457
	v_max_f32_e32 v108, v108, v108
	v_max_f32_e32 v109, v220, v220
	v_max_f32_e32 v108, v109, v108
	v_sub_f32_e32 v109, v220, v108
	v_exp_f32_e32 v109, v109
	v_mov_b32_e32 v220, v108
	v_mul_f32 v48, v48, v109
	v_mul_f32 v49, v49, v109
	v_mul_f32_e32 v211, v211, v109
	v_mul_f32 v50, v50, v109
	v_mul_f32 v51, v51, v109
	v_mul_f32 v52, v52, v109
	v_mul_f32 v53, v53, v109
	v_mul_f32 v54, v54, v109
	v_mul_f32 v55, v55, v109
	v_mul_f32 v56, v56, v109
	v_mul_f32 v57, v57, v109
	v_mul_f32 v58, v58, v109
	v_mul_f32 v59, v59, v109
	v_mul_f32 v60, v60, v109
	v_mul_f32 v61, v61, v109
	v_mul_f32 v62, v62, v109
	v_mul_f32 v63, v63, v109
	v_mul_f32 v32, v32, v109
	v_mul_f32 v33, v33, v109
	v_mul_f32 v34, v34, v109
	v_mul_f32 v35, v35, v109
	v_mul_f32 v36, v36, v109
	v_mul_f32 v37, v37, v109
	v_mul_f32 v38, v38, v109
	v_mul_f32 v39, v39, v109
	v_mul_f32 v40, v40, v109
	v_mul_f32 v41, v41, v109
	v_mul_f32 v42, v42, v109
	v_mul_f32 v43, v43, v109
	v_mul_f32 v44, v44, v109
	v_mul_f32 v45, v45, v109
	v_mul_f32 v46, v46, v109
	v_mul_f32 v47, v47, v109
	v_mul_f32 v16, v16, v109
	v_mul_f32 v17, v17, v109
	v_mul_f32 v18, v18, v109
	v_mul_f32 v19, v19, v109
	v_mul_f32 v20, v20, v109
	v_mul_f32 v21, v21, v109
	v_mul_f32 v22, v22, v109
	v_mul_f32 v23, v23, v109
	v_mul_f32 v24, v24, v109
	v_mul_f32 v25, v25, v109
	v_mul_f32 v26, v26, v109
	v_mul_f32 v27, v27, v109
	v_mul_f32 v28, v28, v109
	v_mul_f32 v29, v29, v109
	v_mul_f32 v30, v30, v109
	v_mul_f32 v31, v31, v109
	v_mul_f32 v0, v0, v109
	v_mul_f32 v1, v1, v109
	v_mul_f32 v2, v2, v109
	v_mul_f32 v3, v3, v109
	v_mul_f32 v4, v4, v109
	v_mul_f32 v5, v5, v109
	v_mul_f32 v6, v6, v109
	v_mul_f32 v7, v7, v109
	v_mul_f32 v8, v8, v109
	v_mul_f32 v9, v9, v109
	v_mul_f32 v10, v10, v109
	v_mul_f32 v11, v11, v109
	v_mul_f32 v12, v12, v109
	v_mul_f32 v13, v13, v109
	v_mul_f32 v14, v14, v109
	v_mul_f32 v15, v15, v109

; __device__ __forceinline__ void attn_unit(LAS unsigned char* lds, int b, int h, int qb, const bf16_t* Q, const bf16_t* KF, const bf16_t* VT,
;                                           const float* gout, bf16_t* MIXED, int wave, int lane) {
;     ...
;     for (int kt = 0; kt < nkt; ++kt) {
;         if (kt + 1 < nkt) ATT_ISSUE(kt + 1, (kt + 1) & 1);
;         const int key0 = kt * 64;
;         if (key0 <= q0w + 31) {
;     ...
;         __syncthreads();
;     }
.LBB0_458:
	s_add_i32 s80, s80, 64
	s_add_u32 s62, s62, 0x30000
	s_addc_u32 s63, s63, 0
	s_add_u32 s52, s52, 0x80
	s_addc_u32 s53, s53, 0
	s_mov_b32 s85, s88
	s_cmp_eq_u32 s71, s80
	s_waitcnt vmcnt(0) lgkmcnt(0)
	s_barrier
	s_cbranch_scc0 .LBB0_440

; __device__ __forceinline__ void attn_unit(LAS unsigned char* lds, int b, int h, int qb, const bf16_t* Q, const bf16_t* KF, const bf16_t* VT,
;                                           const float* gout, bf16_t* MIXED, int wave, int lane) {
;     ...
;             float mt = sacc[0][0];
; #pragma unroll
;             for (int kb = 0; kb < 2; ++kb)
; #pragma unroll
;                 for (int i = 0; i < 16; ++i) mt = fmaxf(mt, sacc[kb][i]);
;             mt = fmaxf(mt, __shfl_xor(mt, 32));
;             __builtin_amdgcn_sched_barrier(0);
;             if (__builtin_amdgcn_ballot_w64(mt > m_run + 8.f) != 0ull) {
;                 const float mn = fmaxf(m_run, mt);
;                 const float alpha = __builtin_amdgcn_exp2f(m_run - mn);
;                 m_run = mn;
;                 l_run *= alpha;
; #pragma unroll
;                 for (int db = 0; db < 4; ++db)
; #pragma unroll
;                     for (int i = 0; i < 16; ++i) asm volatile("v_mul_f32 %0, %0, %1" : "+v"(oacc[db][i]) : "v"(alpha));
;             }
.LBB0_508:
	v_max_f32_e32 v110, v64, v65
	v_max3_f32 v110, v110, v66, v67
	v_max3_f32 v110, v110, v68, v69
	v_max3_f32 v110, v110, v70, v71
	v_max3_f32 v110, v110, v72, v73
	v_max3_f32 v110, v110, v74, v75
	v_max3_f32 v110, v110, v76, v77
	v_max3_f32 v110, v110, v78, v79
	v_max3_f32 v110, v110, v80, v81
	v_max3_f32 v110, v110, v82, v83
	v_max3_f32 v110, v110, v84, v85
	v_max3_f32 v110, v110, v86, v87
	v_max3_f32 v110, v110, v88, v89
	v_max3_f32 v110, v110, v90, v91
	v_max3_f32 v110, v110, v92, v93
	v_max3_f32 v110, v110, v94, v95
	v_mov_b32_e32 v111, v110
	s_nop 1
	v_permlane32_swap_b32_e32 v111, v110
	v_max_f32_e32 v110, v110, v111
	v_add_f32_e32 v111, 0x41000000, v220
	v_cmp_gt_f32_e32 vcc, v110, v111
	s_cbranch_vccz .LBB0_510
	v_max_f32_e32 v110, v110, v110
	v_max_f32_e32 v111, v220, v220
	v_max_f32_e32 v110, v111, v110
	v_sub_f32_e32 v111, v220, v110
	v_exp_f32_e32 v111, v111
	v_mov_b32_e32 v220, v110
	v_mul_f32 v48, v48, v111
	v_mul_f32 v49, v49, v111
	v_mul_f32_e32 v211, v211, v111
	v_mul_f32 v50, v50, v111
	v_mul_f32 v51, v51, v111
	v_mul_f32 v52, v52, v111
	v_mul_f32 v53, v53, v111
	v_mul_f32 v54, v54, v111
	v_mul_f32 v55, v55, v111
	v_mul_f32 v56, v56, v111
	v_mul_f32 v57, v57, v111
	v_mul_f32 v58, v58, v111
	v_mul_f32 v59, v59, v111
	v_mul_f32 v60, v60, v111
	v_mul_f32 v61, v61, v111
	v_mul_f32 v62, v62, v111
	v_mul_f32 v63, v63, v111
	v_mul_f32 v32, v32, v111
	v_mul_f32 v33, v33, v111
	v_mul_f32 v34, v34, v111
	v_mul_f32 v35, v35, v111
	v_mul_f32 v36, v36, v111
	v_mul_f32 v37, v37, v111
	v_mul_f32 v38, v38, v111
	v_mul_f32 v39, v39, v111
	v_mul_f32 v40, v40, v111
	v_mul_f32 v41, v41, v111
	v_mul_f32 v42, v42, v111
	v_mul_f32 v43, v43, v111
	v_mul_f32 v44, v44, v111
	v_mul_f32 v45, v45, v111
	v_mul_f32 v46, v46, v111
	v_mul_f32 v47, v47, v111
	v_mul_f32 v16, v16, v111
	v_mul_f32 v17, v17, v111
	v_mul_f32 v18, v18, v111
	v_mul_f32 v19, v19, v111
	v_mul_f32 v20, v20, v111
	v_mul_f32 v21, v21, v111
	v_mul_f32 v22, v22, v111
	v_mul_f32 v23, v23, v111
	v_mul_f32 v24, v24, v111
	v_mul_f32 v25, v25, v111
	v_mul_f32 v26, v26, v111
	v_mul_f32 v27, v27, v111
	v_mul_f32 v28, v28, v111
	v_mul_f32 v29, v29, v111
	v_mul_f32 v30, v30, v111
	v_mul_f32 v31, v31, v111
	v_mul_f32 v0, v0, v111
	v_mul_f32 v1, v1, v111
	v_mul_f32 v2, v2, v111
	v_mul_f32 v3, v3, v111
	v_mul_f32 v4, v4, v111
	v_mul_f32 v5, v5, v111
	v_mul_f32 v6, v6, v111
	v_mul_f32 v7, v7, v111
	v_mul_f32 v8, v8, v111
	v_mul_f32 v9, v9, v111
	v_mul_f32 v10, v10, v111
	v_mul_f32 v11, v11, v111
	v_mul_f32 v12, v12, v111
	v_mul_f32 v13, v13, v111
	v_mul_f32 v14, v14, v111
	v_mul_f32 v15, v15, v111

; __device__ __forceinline__ void attn_unit(LAS unsigned char* lds, int b, int h, int qb, const bf16_t* Q, const bf16_t* KF, const bf16_t* VT,
;                                           const float* gout, bf16_t* MIXED, int wave, int lane) {
;     ...
;     for (int kt = 0; kt < nkt; ++kt) {
;         if (kt + 1 < nkt) ATT_ISSUE(kt + 1, (kt + 1) & 1);
;         const int key0 = kt * 64;
;         if (key0 <= q0w + 31) {
;     ...
;         __syncthreads();
;     }
.LBB0_511:
	s_add_i32 s22, s22, 64
	s_add_u32 s18, s18, 0x30000
	s_addc_u32 s19, s19, 0
	s_add_u32 s16, s16, 0x80
	s_addc_u32 s17, s17, 0
	s_mov_b32 s25, s24
	s_cmp_eq_u32 s20, s22
	s_waitcnt vmcnt(0) lgkmcnt(0)
	s_barrier
	s_cbranch_scc0 .LBB0_493
